# one static s_setprio 1 for waves 4-7 during the two attention phases (reset at phase end)
# speedup vs baseline: 1.0039x; 1.0039x over previous
; #define LAS __attribute__((address_space(3)))
; __global__ void __launch_bounds__(NWAVES * 64, 2) mk_fwd(Args args) {
;     ...
;                 if (l == 1) {
;                     const float* cs2 = (const float*)(ws + WS_CS2); const unsigned* kmax2 = (const unsigned*)(ws + WS_BTOT) + 2048;
;                     volatile LAS unsigned* qslot = (volatile LAS unsigned*)(lds3 + RING_OFF + attn_body::ATTN_LDS_BYTES);
; #pragma unroll 1
;                     for (;;) { if (tid == 0) *qslot = __hip_atomic_fetch_add((unsigned*)(ws + WS_CTL) + CW_QUEUE, 1u, __ATOMIC_RELAXED, __HIP_MEMORY_SCOPE_AGENT);
;                         __syncthreads(); const unsigned idx = *qslot; __syncthreads();
;                         if (idx >= 2048u + 256u) break;
;                         if (idx >= 256u) { const unsigned iu = idx - 256u; const int qb = 31 - (int)(iu >> 6), bh = (int)(iu & 63u);
;                             const float kmx = sqrtf(__uint_as_float(__hip_atomic_load(kmax2 + bh, __ATOMIC_RELAXED, __HIP_MEMORY_SCOPE_AGENT))) * 1.01f;
;     ...
;                             attn_body::attn_unit<0, 8>(bh >> 4, bh & 15, qb, Qb, Kb, Vb, (attn_body::bf16*)(ws + WS_OB), (char*)lds + RING_OFF, cs2 + (size_t)bh * 8192, nullptr, kmx);
;     ...
;                         } else { const int u = (int)idx;
;     ...
;                             sample_unit<1>(u >> 4, u & 15, lds3 + RING_OFF, A);
;     ...
;                         } }
;                 } else {
;                     int prev_bh = -1;
; #pragma unroll 1
;                     for (int u = bx * (2048 / 256); u < 2048; u += G * (2048 / 256)) {
; #pragma unroll 1
;                         for (int i = 0; i < 2048 / 256; ++i) { const int bh = (u + i) >> 5, qb = (u + i) & 31;
.LBB0_65:
	s_add_u32 s2, s78, 0x13900000
	v_writelane_b32 v255, s2, 48
	s_addc_u32 s2, s79, 0
	v_writelane_b32 v255, s2, 50
	s_mov_b64 s[4:5], -1
	v_readlane_b32 s2, v255, 38
	s_cmp_lg_u32 s2, 1
	s_cbranch_scc0 .LBB0_193
	s_cmpk_gt_i32 s96, 0xff
	s_cbranch_scc1 .LBB0_192
	s_lshl_b32 s27, s96, 3
	s_add_u32 s4, s78, 0x1b900000
	s_addc_u32 s5, s79, 0
	s_lshl_b32 s2, s14, 3
	v_writelane_b32 v255, s2, 52
	s_mov_b32 s59, -1
	v_readfirstlane_b32 s2, v212
	s_nop 3
	s_cmpk_lt_u32 s2, 0x100
	s_cbranch_scc1 .Lprio_b
	s_setprio 1
.Lprio_b:
	s_branch .LBB0_69
.LBB0_68:
	v_readlane_b32 s2, v255, 52
	s_add_i32 s27, s27, s2
	s_cmpk_gt_i32 s27, 0x7ff
	s_cbranch_scc1 .LBB0_167

; #define LAS __attribute__((address_space(3)))
; __global__ void __launch_bounds__(NWAVES * 64, 2) mk_fwd(Args args) {
;     ...
;                 if (l == 1) {
;                     const float* cs2 = (const float*)(ws + WS_CS2); const unsigned* kmax2 = (const unsigned*)(ws + WS_BTOT) + 2048;
;                     volatile LAS unsigned* qslot = (volatile LAS unsigned*)(lds3 + RING_OFF + attn_body::ATTN_LDS_BYTES);
; #pragma unroll 1
;                     for (;;) { if (tid == 0) *qslot = __hip_atomic_fetch_add((unsigned*)(ws + WS_CTL) + CW_QUEUE, 1u, __ATOMIC_RELAXED, __HIP_MEMORY_SCOPE_AGENT);
;                         __syncthreads(); const unsigned idx = *qslot; __syncthreads();
;                         if (idx >= 2048u + 256u) break;
;                         if (idx >= 256u) { const unsigned iu = idx - 256u; const int qb = 31 - (int)(iu >> 6), bh = (int)(iu & 63u);
;                             const float kmx = sqrtf(__uint_as_float(__hip_atomic_load(kmax2 + bh, __ATOMIC_RELAXED, __HIP_MEMORY_SCOPE_AGENT))) * 1.01f;
.LBB0_193:
	s_andn2_b64 vcc, exec, s[4:5]
	s_cbranch_vccnz .LBB0_348
	s_add_u32 s90, s78, 0x1e3c00
	s_addc_u32 s91, s79, 0
	s_add_u32 s4, s78, 0x10000
	s_addc_u32 s5, s79, 0
	s_add_u32 s88, s76, 0x19500000
	v_writelane_b32 v255, s4, 52
	s_addc_u32 s2, s77, 0
	v_cmp_eq_u32_e64 s[40:41], 0, v228
	v_writelane_b32 v255, s5, 53
	s_add_u32 s4, s76, 0x19600000
	v_writelane_b32 v255, s2, 54
	s_addc_u32 s5, s77, 0
	v_writelane_b32 v255, s4, 55
	s_add_u32 s2, s76, 0x19700000
	s_nop 0
	v_writelane_b32 v255, s5, 56
	v_writelane_b32 v255, s2, 57
	s_addc_u32 s2, s77, 0
	s_add_u32 s8, s78, 0x1b900000
	s_addc_u32 s9, s79, 0
	v_writelane_b32 v255, s2, 58
	s_add_u32 s2, s78, 0x200000
	v_writelane_b32 v255, s2, 59
	s_addc_u32 s2, s79, 0
	v_writelane_b32 v255, s2, 60
	v_readfirstlane_b32 s6, v212
	s_nop 3
	s_cmpk_lt_u32 s6, 0x100
	s_cbranch_scc1 .Lprio_f
	s_setprio 1
.Lprio_f:
	v_readlane_b32 s6, v255, 52
	v_readlane_b32 s7, v255, 53
	s_and_saveexec_b64 s[42:43], s[40:41]
	s_cbranch_execz .Lfq_first
	s_nop 3
	global_atomic_add v248, v3, v216, s[6:7] sc0

; __device__ __forceinline__ void xcd_barrier(const XcdBarrier& b) {
;     asm volatile("s_waitcnt vmcnt(0)" ::: "memory");
;     __syncthreads();
;     if (threadIdx.x == 0) {
;         unsigned* bar = b.bar;
;         __builtin_amdgcn_s_waitcnt(0);
;         unsigned nloc = b.st[0], nx = b.st[1];
;         if (nloc == 0u) { xcd_barrier_complete(bar, b.x, nloc, nx); b.st[0] = nloc; b.st[1] = nx; }
; __global__ void __launch_bounds__(NWAVES * 64, 2) mk_fwd(Args args) {
;     ...
;         const bool again = (((PROBE_MASK >> p) & 1u) != 0u) && rep == 0;
;         if (did && (p + 1 < args.ph_hi || again)) {
;             if (p == 0 && !again) { __syncthreads(); cg::this_grid().sync(); } else xcd_barrier(bar);
.LBB0_735:
	s_setprio 0
	s_and_b64 vcc, exec, s[4:5]
	s_cbranch_vccz .LBB0_17
	s_add_i32 s27, s72, 1
	s_cmp_ge_i32 s27, s73
	s_cbranch_scc1 .LBB0_17
	s_waitcnt vmcnt(0)
	s_waitcnt vmcnt(0) lgkmcnt(0)
	s_barrier
	s_mov_b64 s[0:1], exec
	v_readlane_b32 s4, v255, 27
	v_readlane_b32 s5, v255, 28
	s_and_b64 s[4:5], s[0:1], s[4:5]
	v_readlane_b32 s19, v254, 2
	s_mov_b64 exec, s[4:5]
	s_cbranch_execz .LBB0_787
	v_mov_b32_e32 v0, s19
	s_waitcnt vmcnt(0) expcnt(0) lgkmcnt(0)
	ds_read_b32 v2, v0
	ds_read_b32 v0, v0 offset:4
	s_waitcnt lgkmcnt(1)
	v_cmp_ne_u32_e32 vcc, 0, v2
	s_cbranch_vccnz .LBB0_755
	v_readlane_b32 s6, v254, 3
	v_readlane_b32 s7, v254, 4
	s_load_dwordx2 s[4:5], s[6:7], 0x4
	v_readlane_b32 s2, v255, 32
	s_mov_b32 s14, 1
	s_waitcnt lgkmcnt(0)
	s_mul_i32 s2, s4, s2
	s_mul_i32 s2, s2, s5
	s_branch .LBB0_742
